# strategy 4: one static s_setprio 1 for waves 4-7 in the attention phases, per-cluster toggles neutralised (s_nop 0 in place)
# speedup vs baseline: 1.0068x; 1.0047x over previous
; DI void phase_diff(const Params& p, char* smem, int tid0) {
;   int tid = tid0;
;   float s1 = 0.f, s2 = 0.f;
;   for (int i = 0; i < 64; ++i) { s1 += p.lq1[i] * p.lk1[i]; s2 += p.lq2[i] * p.lk2[i]; }
;   const float lam = expf(s1) - expf(s2) + 0.2f;
;   int* s_item = (int*)(smem + SMEM_BYTES - 16);
;   int nxt = 0;
;   if (tid == 0) nxt = atomicAdd(p.ctr, 1);
.LBB0_548:
	s_or_b64 exec, exec, s[0:1]
	v_mul_f32_e32 v2, 0x3fb8aa3b, v0
	s_mov_b32 s0, 0x3fb8aa3b
	v_rndne_f32_e32 v3, v2
	v_sub_f32_e32 v4, v2, v3
	v_fma_f32 v2, v0, s0, -v2
	v_fmac_f32_e32 v2, 0x32a5705f, v0
	v_add_f32_e32 v2, v4, v2
	v_exp_f32_e32 v2, v2
	v_cvt_i32_f32_e32 v3, v3
	s_mov_b32 s2, 0xc2ce8ed0
	v_cmp_ngt_f32_e32 vcc, s2, v0
	s_mov_b32 s3, 0x42b17218
	v_ldexp_f32 v2, v2, v3
	v_mul_f32_e32 v3, 0x3fb8aa3b, v1
	v_rndne_f32_e32 v4, v3
	v_sub_f32_e32 v5, v3, v4
	v_fma_f32 v3, v1, s0, -v3
	v_fmac_f32_e32 v3, 0x32a5705f, v1
	v_add_f32_e32 v3, v5, v3
	v_exp_f32_e32 v3, v3
	v_cvt_i32_f32_e32 v4, v4
	v_cndmask_b32_e32 v2, 0, v2, vcc
	v_mov_b32_e32 v5, 0x7f800000
	v_cmp_nlt_f32_e32 vcc, s3, v0
	s_mov_b32 s1, 0
	s_mov_b64 s[30:31], 0x80
	v_cndmask_b32_e32 v0, v5, v2, vcc
	v_ldexp_f32 v2, v3, v4
	v_cmp_ngt_f32_e32 vcc, s2, v1
	s_movk_i32 s40, 0x83f
	v_mov_b32_e32 v179, 0
	v_cndmask_b32_e32 v2, 0, v2, vcc
	v_cmp_nlt_f32_e32 vcc, s3, v1
	s_load_dwordx8 s[16:23], s[92:93], 0xd0
	s_load_dwordx2 s[2:3], s[92:93], 0x50
	s_load_dwordx2 s[24:25], s[92:93], 0xc0
	s_load_dwordx2 s[4:5], s[92:93], 0xf0
	s_load_dwordx2 s[26:27], s[92:93], 0x170
	s_load_dwordx2 s[28:29], s[92:93], 0x140
	v_cndmask_b32_e32 v1, v5, v2, vcc
	v_sub_f32_e32 v0, v0, v1
	s_waitcnt lgkmcnt(0)
	s_add_u32 s34, s24, 0x80
	v_writelane_b32 v255, s4, 6
	s_addc_u32 s35, s25, 0
	s_add_i32 s33, 0, 0x247f0
	v_add_f32_e32 v192, 0x3e4ccccd, v0
	v_writelane_b32 v255, s5, 7
	v_mov_b32_e32 v193, s33
	s_movk_i32 s41, 0xf0
	s_movk_i32 s52, 0x70
	s_mov_b32 s53, 0xf149f2ca
	s_mov_b32 s54, 0xefa18f08
	s_movk_i32 s55, 0x100
	v_mov_b32_e32 v194, 0x358637bd
	s_mov_b32 s56, 0x800000
	s_movk_i32 s57, 0x108
	s_mov_b32 s58, 0x80402011
	s_mov_b64 s[36:37], 0x80000
	v_mov_b32_e32 v195, 0xf149f2ca
	v_mbcnt_hi_u32_b32 v230, -1, v153
	v_readfirstlane_b32 s98, v197
	s_nop 3
	s_lshr_b32 s98, s98, 8
	s_cmp_lg_u32 s98, 0
	s_cbranch_scc0 .Lprio_p3
	s_setprio 1
.Lprio_p3:
	s_branch .LBB0_551
.LBB0_549:
	s_mov_b64 s[6:7], 0

; DI unsigned pk2(float a, float b) { f32x2 v = {a, b}; bf16x2_t r = __builtin_convertvector(v, bf16x2_t); return __builtin_bit_cast(unsigned, r); }
; DI f32x4 mfma16(bf16x8 a, bf16x8 b, f32x4 c) { return __builtin_amdgcn_mfma_f32_16x16x32_bf16(a, b, c, 0, 0, 0); }
; #define SB0 __builtin_amdgcn_sched_barrier(0)
; DI void diff_PV(f32x4 (&o0)[8], f32x4 (&o1)[8], const char* Vb, const bf16x8 (&p0)[2], const bf16x8 (&p1)[2], bf16x8 (&v0)[4], bf16x8 (&v1)[4], int lr, int quad) {
;   bf16x8 v2[4], v3[4];
;   SB0;
;   ldv4(v2, Vb, 2, lr, quad);
;   __builtin_amdgcn_s_setprio(1);
; #pragma unroll
;   for (int i = 0; i < 4; ++i) { o0[i] = mfma16(v0[i], p0[0], o0[i]); o1[i] = mfma16(v0[i], p1[0], o1[i]); }
;   __builtin_amdgcn_s_setprio(0);
;   SB0;
;   ldv4(v3, Vb, 3, lr, quad);
;   __builtin_amdgcn_s_setprio(1);
; #pragma unroll
;   for (int i = 0; i < 4; ++i) { o0[4 + i] = mfma16(v1[i], p0[0], o0[4 + i]); o1[4 + i] = mfma16(v1[i], p1[0], o1[4 + i]); }
;   __builtin_amdgcn_s_setprio(0);
;   SB0;
;   __builtin_amdgcn_s_setprio(1);
; #pragma unroll
;   for (int i = 0; i < 4; ++i) { o0[i] = mfma16(v2[i], p0[1], o0[i]); o1[i] = mfma16(v2[i], p1[1], o1[i]); }
;   __builtin_amdgcn_s_setprio(0);
;   __builtin_amdgcn_s_setprio(1);
; #pragma unroll
;   for (int i = 0; i < 4; ++i) { o0[4 + i] = mfma16(v3[i], p0[1], o0[4 + i]); o1[4 + i] = mfma16(v3[i], p1[1], o1[4 + i]); }
;   __builtin_amdgcn_s_setprio(0);
; }
; DI void pack_p(const f32x4 (&s)[4], bf16x8 (&pf)[2]) {
; #pragma unroll
;   for (int s2 = 0; s2 < 2; ++s2)
;     pf[s2] = mk8(pk2(s[2 * s2][0], s[2 * s2][1]), pk2(s[2 * s2][2], s[2 * s2][3]),
;                  pk2(s[2 * s2 + 1][0], s[2 * s2 + 1][1]), pk2(s[2 * s2 + 1][2], s[2 * s2 + 1][3]));
; }
.LBB0_569:
	s_or_b64 exec, exec, s[50:51]
	v_add_f32_e32 v219, v219, v231
	v_cvt_pk_bf16_f32 v0, v0, v1
	v_cvt_pk_bf16_f32 v1, v2, v3
	v_cvt_pk_bf16_f32 v2, v4, v5
	v_cvt_pk_bf16_f32 v3, v6, v7
	v_cvt_pk_bf16_f32 v4, v8, v9
	v_cvt_pk_bf16_f32 v5, v10, v11
	v_cvt_pk_bf16_f32 v6, v12, v13
	v_cvt_pk_bf16_f32 v7, v14, v15
	v_cvt_pk_bf16_f32 v8, v16, v17
	v_cvt_pk_bf16_f32 v9, v18, v19
	v_cvt_pk_bf16_f32 v10, v20, v21
	v_cvt_pk_bf16_f32 v11, v22, v23
	v_cvt_pk_bf16_f32 v12, v24, v25
	v_cvt_pk_bf16_f32 v13, v26, v27
	v_cvt_pk_bf16_f32 v14, v28, v29
	v_cvt_pk_bf16_f32 v15, v30, v31
	v_add3_u32 v144, s67, v218, v216
	ds_read_b128 v[16:19], v144 offset:16384
	ds_read_b128 v[20:23], v144 offset:18432
	ds_read_b128 v[24:27], v144 offset:20480
	ds_read_b128 v[28:31], v144 offset:22528
	s_nop 0
	s_waitcnt lgkmcnt(4)
	v_mfma_f32_16x16x32_bf16 v[92:95], v[140:143], v[0:3], v[92:95]
	v_mfma_f32_16x16x32_bf16 v[60:63], v[140:143], v[8:11], v[60:63]
	v_mfma_f32_16x16x32_bf16 v[88:91], v[136:139], v[0:3], v[88:91]
	v_mfma_f32_16x16x32_bf16 v[56:59], v[136:139], v[8:11], v[56:59]
	v_mfma_f32_16x16x32_bf16 v[84:87], v[128:131], v[0:3], v[84:87]
	v_mfma_f32_16x16x32_bf16 v[52:55], v[128:131], v[8:11], v[52:55]
	v_mfma_f32_16x16x32_bf16 v[80:83], v[120:123], v[0:3], v[80:83]
	v_mfma_f32_16x16x32_bf16 v[48:51], v[120:123], v[8:11], v[48:51]
	s_nop 0
	ds_read_b128 v[120:123], v144 offset:24576
	ds_read_b128 v[128:131], v144 offset:26624
	ds_read_b128 v[136:139], v144 offset:28672
	ds_read_b128 v[140:143], v144 offset:30720
	s_nop 0
	v_mfma_f32_16x16x32_bf16 v[76:79], v[132:135], v[0:3], v[76:79]
	v_mfma_f32_16x16x32_bf16 v[44:47], v[132:135], v[8:11], v[44:47]
	v_mfma_f32_16x16x32_bf16 v[72:75], v[124:127], v[0:3], v[72:75]
	v_mfma_f32_16x16x32_bf16 v[40:43], v[124:127], v[8:11], v[40:43]
	v_mfma_f32_16x16x32_bf16 v[68:71], v[116:119], v[0:3], v[68:71]
	v_mfma_f32_16x16x32_bf16 v[36:39], v[116:119], v[8:11], v[36:39]
	v_mfma_f32_16x16x32_bf16 v[0:3], v[112:115], v[0:3], v[64:67]
	v_mfma_f32_16x16x32_bf16 v[8:11], v[112:115], v[8:11], v[32:35]
	s_nop 0
	s_nop 0
	s_waitcnt lgkmcnt(7)
	v_mfma_f32_16x16x32_bf16 v[92:95], v[16:19], v[4:7], v[92:95]
	v_mfma_f32_16x16x32_bf16 v[60:63], v[16:19], v[12:15], v[60:63]
	s_waitcnt lgkmcnt(6)
	v_mfma_f32_16x16x32_bf16 v[88:91], v[20:23], v[4:7], v[88:91]
	v_mfma_f32_16x16x32_bf16 v[56:59], v[20:23], v[12:15], v[56:59]
	s_waitcnt lgkmcnt(5)
	v_mfma_f32_16x16x32_bf16 v[84:87], v[24:27], v[4:7], v[84:87]
	v_mfma_f32_16x16x32_bf16 v[52:55], v[24:27], v[12:15], v[52:55]
	s_waitcnt lgkmcnt(4)
	v_mfma_f32_16x16x32_bf16 v[80:83], v[28:31], v[4:7], v[80:83]
	v_mfma_f32_16x16x32_bf16 v[48:51], v[28:31], v[12:15], v[48:51]
	s_nop 0
	s_nop 0
	s_waitcnt lgkmcnt(3)
	v_mfma_f32_16x16x32_bf16 v[76:79], v[120:123], v[4:7], v[76:79]
	v_mfma_f32_16x16x32_bf16 v[44:47], v[120:123], v[12:15], v[44:47]
	s_waitcnt lgkmcnt(2)
	v_mfma_f32_16x16x32_bf16 v[72:75], v[128:131], v[4:7], v[72:75]
	v_mfma_f32_16x16x32_bf16 v[40:43], v[128:131], v[12:15], v[40:43]
	s_waitcnt lgkmcnt(1)
	v_mfma_f32_16x16x32_bf16 v[68:71], v[136:139], v[4:7], v[68:71]
	v_mfma_f32_16x16x32_bf16 v[36:39], v[136:139], v[12:15], v[36:39]
	s_waitcnt lgkmcnt(0)
	v_mfma_f32_16x16x32_bf16 v[64:67], v[140:143], v[4:7], v[0:3]
	v_mfma_f32_16x16x32_bf16 v[32:35], v[140:143], v[12:15], v[8:11]
	s_nop 0

; DI float ex2(float x) { return __builtin_amdgcn_exp2f(x); }
; #define SB0 __builtin_amdgcn_sched_barrier(0)
; template <bool MASKED, class MF>
; DI void flash_update(f32x4 (&s)[4], float scl, float& mx, float& ls, f32x4 (&o)[8], MF maskfn, bool lane_on) {
;   float tmax = -1e30f;
; #pragma unroll
;   for (int kt = 0; kt < 4; ++kt)
; #pragma unroll
;     for (int i = 0; i < 4; ++i) {
;       if (MASKED) { if (maskfn(kt, i)) s[kt][i] = -1e30f; }
;       tmax = fmaxf(tmax, s[kt][i]);
;     }
;   tmax = rowmax4(tmax);
;   if (!lane_on) tmax = -1e30f;
;   const float th = 8.f / scl;
;   if (__any(tmax > mx + th)) {
;     const float mnew = fmaxf(mx, tmax);
;     const float alpha = ex2((mx - mnew) * scl);
;     ls *= alpha;
; #pragma unroll
;     for (int dt = 0; dt < 8; ++dt) o[dt] *= alpha;
;     mx = mnew;
;   }
; DI void ldk2m(bf16x8 (&k)[2], const char* Kb, int m, int kt, int lr, int quad) {
; #pragma unroll
;   for (int kk = 0; kk < 2; ++kk) k[kk] = *(const bf16x8*)(Kb + (kt * 16 + lr) * 256 + (((m * 8 + kk * 4 + quad) ^ lr) << 4));
; }
; DI void diff_S2(f32x4 (&s0)[4], f32x4 (&s1)[4], const char* Kb, const char* Vb, int m, const bf16x8 (&q0)[2], const bf16x8 (&q1)[2],
;                 bf16x8 (&v0)[4], bf16x8 (&v1)[4], int lr, int quad) {
;   bf16x8 f0[2], f1[2], f2[2], f3[2];
;   ldk2m(f0, Kb, m, 0, lr, quad); ldk2m(f1, Kb, m, 1, lr, quad); SB0;
;   ldk2m(f2, Kb, m, 2, lr, quad); s0[0] = mma2(f0, q0); s1[0] = mma2(f0, q1); SB0;
;   ldk2m(f3, Kb, m, 3, lr, quad); s0[1] = mma2(f1, q0); s1[1] = mma2(f1, q1); SB0;
;   ldv4(v0, Vb, 0, lr, quad); s0[2] = mma2(f2, q0); s1[2] = mma2(f2, q1); SB0;
;   ldv4(v1, Vb, 1, lr, quad); s0[3] = mma2(f3, q0); s1[3] = mma2(f3, q1); SB0;
; }
.LBB0_571:
	s_cmp_eq_u32 s7, s63
	s_cbranch_scc1 .LBB0_582
	s_or_b32 s4, s7, s65
	s_lshl_b32 s6, s4, 6
	v_cmp_le_u32_e32 vcc, s6, v211
	s_and_saveexec_b64 s[48:49], vcc
	s_cbranch_execz .LBB0_570
	s_lshl_b32 s4, s7, 15
	s_add_i32 s67, s66, s4
	v_add_u32_e32 v0, s67, v212
	v_add_u32_e32 v28, v0, v214
	v_add_u32_e32 v29, v0, v215
	ds_read_b128 v[0:3], v28
	ds_read_b128 v[4:7], v28 offset:4096
	ds_read_b128 v[8:11], v29
	ds_read_b128 v[12:15], v29 offset:4096
	s_or_b32 s4, s6, 63
	v_cmp_le_u32_e32 vcc, s4, v207
	ds_read_b128 v[16:19], v28 offset:8192
	ds_read_b128 v[20:23], v29 offset:8192
	s_nop 0
	s_waitcnt lgkmcnt(5)
	v_mfma_f32_16x16x32_bf16 v[24:27], v[0:3], v[96:99], 0
	s_waitcnt lgkmcnt(3)
	v_mfma_f32_16x16x32_bf16 v[172:175], v[8:11], v[100:103], v[24:27]
	s_nop 0
	s_nop 0
	v_mfma_f32_16x16x32_bf16 v[0:3], v[0:3], v[104:107], 0
	v_mfma_f32_16x16x32_bf16 v[156:159], v[8:11], v[108:111], v[0:3]
	s_nop 0
	s_nop 5
	ds_read_b128 v[0:3], v28 offset:12288
	ds_read_b128 v[8:11], v29 offset:12288
	s_nop 0
	v_mfma_f32_16x16x32_bf16 v[24:27], v[4:7], v[96:99], 0
	s_waitcnt lgkmcnt(4)
	v_mfma_f32_16x16x32_bf16 v[164:167], v[12:15], v[100:103], v[24:27]
	s_nop 0
	s_nop 0
	v_mfma_f32_16x16x32_bf16 v[4:7], v[4:7], v[104:107], 0
	v_mfma_f32_16x16x32_bf16 v[148:151], v[12:15], v[108:111], v[4:7]
	s_nop 0
	v_add3_u32 v12, s67, v217, v216
	ds_read_b128 v[140:143], v12 offset:16384
	ds_read_b128 v[136:139], v12 offset:18432
	ds_read_b128 v[128:131], v12 offset:20480
	ds_read_b128 v[120:123], v12 offset:22528
	s_nop 0
	s_waitcnt lgkmcnt(7)
	v_mfma_f32_16x16x32_bf16 v[4:7], v[16:19], v[96:99], 0
	s_waitcnt lgkmcnt(6)
	v_mfma_f32_16x16x32_bf16 v[168:171], v[20:23], v[100:103], v[4:7]
	s_nop 0
	s_nop 0
	v_mfma_f32_16x16x32_bf16 v[4:7], v[16:19], v[104:107], 0
	v_mfma_f32_16x16x32_bf16 v[152:155], v[20:23], v[108:111], v[4:7]
	s_nop 0
	ds_read_b128 v[132:135], v12 offset:24576
	ds_read_b128 v[124:127], v12 offset:26624
	ds_read_b128 v[116:119], v12 offset:28672
	ds_read_b128 v[112:115], v12 offset:30720
	s_nop 0
	s_waitcnt lgkmcnt(9)
	v_mfma_f32_16x16x32_bf16 v[4:7], v[0:3], v[96:99], 0
	s_waitcnt lgkmcnt(8)
	v_mfma_f32_16x16x32_bf16 v[160:163], v[8:11], v[100:103], v[4:7]
	s_nop 0
	s_nop 0
	v_mfma_f32_16x16x32_bf16 v[0:3], v[0:3], v[104:107], 0
	v_mfma_f32_16x16x32_bf16 v[144:147], v[8:11], v[108:111], v[0:3]
	s_nop 0
	v_add_f32_e32 v232, 0x40b17218, v220
	s_and_saveexec_b64 s[4:5], vcc
	s_xor_b64 s[4:5], exec, s[4:5]
	s_cbranch_execz .LBB0_579
	s_nop 1
	v_max3_f32 v0, v172, s53, v173
	v_max3_f32 v0, v0, v174, v175
	v_max3_f32 v0, v0, v164, v165
	v_max3_f32 v0, v0, v166, v167
	v_max3_f32 v0, v0, v168, v169
	v_max3_f32 v0, v0, v170, v171
	v_max3_f32 v0, v0, v160, v161
	v_max3_f32 v0, v0, v162, v163
	v_mov_b32_e32 v1, v0
	s_nop 1
	v_permlane16_swap_b32_e32 v0, v1
	v_max_f32_e32 v1, v1, v1
	v_max_f32_e32 v0, v0, v0
	v_max_f32_e32 v0, v0, v1
	v_mov_b32_e32 v1, v0
	s_nop 1
	v_permlane32_swap_b32_e32 v0, v1
	v_max_f32_e32 v1, v1, v1
	v_max_f32_e32 v0, v0, v0
	v_max_f32_e32 v0, v0, v1
	v_cmp_gt_f32_e32 vcc, v0, v232
	s_cbranch_vccz .LBB0_576
	v_max_f32_e32 v0, v0, v0
	v_max_f32_e32 v1, v220, v220
	v_max_f32_e32 v1, v1, v0
	v_sub_f32_e32 v0, v220, v1
	v_mul_f32_e32 v0, 0x3fb8aa3b, v0
	v_exp_f32_e32 v0, v0
	v_mov_b32_e32 v220, v1
	v_mul_f32_e32 v213, v213, v0
	v_pk_mul_f32 v[94:95], v[94:95], v[0:1] op_sel_hi:[1,0]
	v_pk_mul_f32 v[92:93], v[92:93], v[0:1] op_sel_hi:[1,0]
	v_pk_mul_f32 v[90:91], v[90:91], v[0:1] op_sel_hi:[1,0]
	v_pk_mul_f32 v[88:89], v[88:89], v[0:1] op_sel_hi:[1,0]
	v_pk_mul_f32 v[86:87], v[86:87], v[0:1] op_sel_hi:[1,0]
	v_pk_mul_f32 v[84:85], v[84:85], v[0:1] op_sel_hi:[1,0]
	v_pk_mul_f32 v[82:83], v[82:83], v[0:1] op_sel_hi:[1,0]
	v_pk_mul_f32 v[80:81], v[80:81], v[0:1] op_sel_hi:[1,0]
	v_pk_mul_f32 v[78:79], v[78:79], v[0:1] op_sel_hi:[1,0]
	v_pk_mul_f32 v[76:77], v[76:77], v[0:1] op_sel_hi:[1,0]
	v_pk_mul_f32 v[74:75], v[74:75], v[0:1] op_sel_hi:[1,0]
	v_pk_mul_f32 v[72:73], v[72:73], v[0:1] op_sel_hi:[1,0]
	v_pk_mul_f32 v[70:71], v[70:71], v[0:1] op_sel_hi:[1,0]
	v_pk_mul_f32 v[68:69], v[68:69], v[0:1] op_sel_hi:[1,0]
	v_pk_mul_f32 v[66:67], v[66:67], v[0:1] op_sel_hi:[1,0]
	v_pk_mul_f32 v[64:65], v[64:65], v[0:1] op_sel_hi:[1,0]

; DI void grid_bar(int* cnt, int target) {
;   __syncthreads();
;   if (threadIdx.x == 0) {
;     __builtin_amdgcn_fence(__ATOMIC_RELEASE, "agent");
;     asm volatile("s_waitcnt vmcnt(0)" ::: "memory");
;     __hip_atomic_fetch_add(cnt, 1, __ATOMIC_RELAXED, __HIP_MEMORY_SCOPE_AGENT);
;     while (__hip_atomic_load(cnt, __ATOMIC_RELAXED, __HIP_MEMORY_SCOPE_AGENT) < target) __builtin_amdgcn_s_sleep(2);
.LBB0_597:
	s_setprio 0
	s_barrier
	s_mov_b64 s[0:1], exec
	s_load_dwordx2 s[34:35], s[92:93], 0x188
	v_readlane_b32 s2, v255, 4
	v_readlane_b32 s3, v255, 5
	s_and_b64 s[2:3], s[0:1], s[2:3]
	s_mov_b64 exec, s[2:3]
	s_cbranch_execz .LBB0_603
	s_mov_b64 s[2:3], exec
	buffer_wbl2 sc1
	s_waitcnt vmcnt(0) lgkmcnt(0)
	s_waitcnt vmcnt(0)
	v_mbcnt_lo_u32_b32 v0, s2, 0
	v_mbcnt_hi_u32_b32 v0, s3, v0
	v_cmp_eq_u32_e32 vcc, 0, v0
	s_and_saveexec_b64 s[4:5], vcc
	s_cbranch_execz .LBB0_600
	s_bcnt1_i32_b64 s2, s[2:3]
	v_mov_b32_e32 v0, 0
	v_mov_b32_e32 v1, s2
	global_atomic_add v0, v1, s[34:35] offset:64

; DI void nsa_item(const Params& p, int b, int g, int qb, char* smem, int tid) {
;   const int lane = tid & 63, wid = tid >> 6, lr = lane & 15, quad = lane >> 4;
;   const int hh = lr & 3, qi = wid * 4 + (lr >> 2), h = g * 4 + hh, bg = b * 2 + g;
;   const int q0 = qb * 32, qp = q0 + qi, cur = q0 >> 6;
;   float* imp = (float*)(smem + 131072);
;   unsigned* sel = (unsigned*)(smem + 131072 + 32 * 132 * 4);
;   const float SCL = 0.08838834764831845f * LOG2E;
;   bf16x8 qf[4];
; #pragma unroll
;   for (int kk = 0; kk < 4; ++kk) qf[kk] = *(const bf16x8*)(p.Qb + (size_t)(b * SQ + qp) * 1024 + h * 128 + kk * 32 + quad * 8);
;   float gt[3];
; #pragma unroll
;   for (int br = 0; br < 3; ++br) gt[br] = p.Bg[(size_t)(b * SQ + qp) * 24 + h * 3 + br];
;   uint2 oc[8];
;   f32x4 o[8];
; #pragma unroll
;   for (int dt = 0; dt < 8; ++dt) { oc[dt] = make_uint2(0u, 0u); o[dt] = zero4(); }
;   __syncthreads();
;   for (int i = tid; i < 32 * 132; i += NTHR) imp[i] = 0.f;
;   if (tid < 128) sel[tid] = 0u;
;   const u16* kcb = p.Kc + (size_t)bg * 512 * 128;
;   const u16* vcb = p.VcT + (size_t)bg * 128 * 512;
;   const int ncv = q0 / 16 + 1;
;   const int nct = (ncv + 63) >> 6;
;   const int cmax = (qp - 31) >> 4;
;   float mx = -1e30f, ls = 0.f;
; DI void phase_nsa(const Params& p, char* smem, int tid0) {
;   int tid = tid0;
;   int* s_item = (int*)(smem + SMEM_BYTES - 16);
;   int nxt = 0;
;   if (tid == 0) nxt = atomicAdd(p.ctr + 1, 1);
.LBB0_728:
	s_or_b64 exec, exec, s[0:1]
	s_and_b32 s0, s90, 7
	s_lshl_b32 s0, s0, 2
	s_mov_b32 s1, 0
	v_lshl_add_u64 v[206:207], s[0:1], 0, v[206:207]
	s_add_i32 s0, 0, 0x20004
	v_writelane_b32 v255, s0, 8
	v_writelane_b32 v255, s90, 9
	s_load_dwordx4 s[60:63], s[92:93], 0x148
	s_load_dwordx8 s[64:71], s[92:93], 0x110
	v_writelane_b32 v255, s92, 10
	s_add_i32 s72, 0, 0x247f0
	s_add_i32 s76, 0, 0x20000
	v_writelane_b32 v255, s93, 11
	v_writelane_b32 v255, s94, 12
	s_mov_b32 s1, 0
	v_mov_b32_e32 v203, s72
	v_writelane_b32 v255, s95, 13
	s_waitcnt lgkmcnt(0)
	v_writelane_b32 v255, s60, 14
	s_movk_i32 s73, 0x7ff
	v_mov_b32_e32 v205, 1
	v_writelane_b32 v255, s61, 15
	v_writelane_b32 v255, s62, 16
	v_writelane_b32 v255, s63, 17
	v_writelane_b32 v255, s64, 18
	v_mov_b32_e32 v17, 0
	s_movk_i32 s74, 0x60
	v_writelane_b32 v255, s65, 19
	v_writelane_b32 v255, s66, 20
	v_writelane_b32 v255, s67, 21
	v_writelane_b32 v255, s68, 22
	v_writelane_b32 v255, s69, 23
	v_writelane_b32 v255, s70, 24
	v_writelane_b32 v255, s71, 25
	v_writelane_b32 v255, s72, 26
	s_movk_i32 s75, 0x1080
	s_movk_i32 s77, 0xe7f
	s_movk_i32 s78, 0x80
	s_movk_i32 s79, 0xf0
	s_movk_i32 s80, 0x70
	s_mov_b64 s[82:83], 0x80
	s_mov_b32 s81, 0x10000
	s_mov_b32 s40, 0x3e0293ee
	s_mov_b32 s41, 0xf149f2ca
	s_mov_b32 s33, 0xefa18f08
	s_movk_i32 s84, 0x210
	v_mov_b32_e32 v231, 0xf149f2ca
	v_mov_b32_e32 v232, 0x461c4000
	v_writelane_b32 v255, s76, 27
	v_readfirstlane_b32 s98, v197
	s_nop 3
	s_lshr_b32 s98, s98, 8
	s_cmp_lg_u32 s98, 0
	s_cbranch_scc0 .Lprio_p5
	s_setprio 1
.Lprio_p5:
	s_branch .LBB0_732
.LBB0_729:
	v_mov_b32_e32 v18, v17
	v_mov_b32_e32 v19, v17
	v_mov_b32_e32 v16, v17
	v_mov_b64_e32 v[128:129], v[18:19]
	v_mov_b64_e32 v[124:125], v[18:19]
	v_mov_b64_e32 v[120:121], v[18:19]
	v_mov_b64_e32 v[116:117], v[18:19]
	v_mov_b64_e32 v[112:113], v[18:19]
	v_mov_b64_e32 v[108:109], v[18:19]
	v_mov_b64_e32 v[104:105], v[18:19]
	v_mov_b64_e32 v[100:101], v[18:19]
	v_mov_b32_e32 v244, 0
	v_mov_b64_e32 v[126:127], v[16:17]
	v_mov_b64_e32 v[122:123], v[16:17]
	v_mov_b64_e32 v[118:119], v[16:17]
	v_mov_b64_e32 v[114:115], v[16:17]
	v_mov_b64_e32 v[110:111], v[16:17]
	v_mov_b64_e32 v[106:107], v[16:17]
	v_mov_b64_e32 v[102:103], v[16:17]
	v_mov_b64_e32 v[98:99], v[16:17]

; DI f32x4 mfma16(bf16x8 a, bf16x8 b, f32x4 c) { return __builtin_amdgcn_mfma_f32_16x16x32_bf16(a, b, c, 0, 0, 0); }
; #define SB0 __builtin_amdgcn_sched_barrier(0)
; DI void ldk4(bf16x8 (&k)[4], const char* Kb, int kt, int lr, int quad) {
; #pragma unroll
;   for (int kk = 0; kk < 4; ++kk) k[kk] = *(const bf16x8*)(Kb + (kt * 16 + lr) * 256 + (((kk * 4 + quad) ^ lr) << 4));
; }
; DI f32x4 mma4(const bf16x8 (&k)[4], const bf16x8 (&qf)[4]) {
;   f32x4 a = zero4();
;   __builtin_amdgcn_s_setprio(1);
; #pragma unroll
;   for (int kk = 0; kk < 4; ++kk) a = mfma16(k[kk], qf[kk], a);
;   __builtin_amdgcn_s_setprio(0);
;   return a;
; }
; DI void ldv4(bf16x8 (&v)[4], const char* Vb, int qtr, int lr, int quad) {
; #pragma unroll
;   for (int i = 0; i < 4; ++i) v[i] = load_vfrag(Vb, qtr >> 1, 4 * (qtr & 1) + i, lr, quad);
; }
; DI void nsa_S(f32x4 (&s)[4], const char* Kb, const char* Vb, const bf16x8 (&qf)[4], bf16x8 (&v0)[4], int lr, int quad) {
;   bf16x8 k0[4], k1[4], k2[4], k3[4];
;   ldk4(k0, Kb, 0, lr, quad); SB0;
;   ldk4(k1, Kb, 1, lr, quad); s[0] = mma4(k0, qf); SB0;
;   ldk4(k2, Kb, 2, lr, quad); s[1] = mma4(k1, qf); SB0;
;   ldk4(k3, Kb, 3, lr, quad); s[2] = mma4(k2, qf); SB0;
;   ldv4(v0, Vb, 0, lr, quad); s[3] = mma4(k3, qf); SB0;
; }
.LBB0_752:
	v_lshl_add_u32 v14, s13, 15, v9
	v_add_u32_e32 v15, v14, v235
	v_add_u32_e32 v67, v14, v237
	v_add_u32_e32 v66, v14, v236
	ds_read_b128 v[10:13], v15
	ds_read_b128 v[34:37], v66
	v_add_u32_e32 v14, v14, v238
	ds_read_b128 v[38:41], v67
	ds_read_b128 v[42:45], v14
	s_xor_b64 s[10:11], s[10:11], -1
	ds_read_b128 v[46:49], v15 offset:4096
	ds_read_b128 v[50:53], v66 offset:4096
	ds_read_b128 v[54:57], v67 offset:4096
	ds_read_b128 v[58:61], v14 offset:4096
	s_nop 0
	s_waitcnt lgkmcnt(7)
	v_mfma_f32_16x16x32_bf16 v[10:13], v[10:13], v[18:21], 0
	s_waitcnt lgkmcnt(6)
	v_mfma_f32_16x16x32_bf16 v[10:13], v[34:37], v[22:25], v[10:13]
	s_waitcnt lgkmcnt(5)
	v_mfma_f32_16x16x32_bf16 v[10:13], v[38:41], v[26:29], v[10:13]
	s_waitcnt lgkmcnt(4)
	v_mfma_f32_16x16x32_bf16 v[10:13], v[42:45], v[30:33], v[10:13]
	s_nop 0
	ds_read_b128 v[34:37], v15 offset:8192
	ds_read_b128 v[38:41], v66 offset:8192
	ds_read_b128 v[42:45], v67 offset:8192
	ds_read_b128 v[62:65], v14 offset:8192
	s_nop 0
	s_waitcnt lgkmcnt(7)
	v_mfma_f32_16x16x32_bf16 v[46:49], v[46:49], v[18:21], 0
	s_waitcnt lgkmcnt(6)
	v_mfma_f32_16x16x32_bf16 v[46:49], v[50:53], v[22:25], v[46:49]
	s_waitcnt lgkmcnt(5)
	v_mfma_f32_16x16x32_bf16 v[46:49], v[54:57], v[26:29], v[46:49]
	s_waitcnt lgkmcnt(4)
	v_mfma_f32_16x16x32_bf16 v[46:49], v[58:61], v[30:33], v[46:49]
	s_nop 0
	ds_read_b128 v[50:53], v15 offset:12288
	ds_read_b128 v[54:57], v66 offset:12288
	ds_read_b128 v[58:61], v67 offset:12288
	ds_read_b128 v[66:69], v14 offset:12288
	s_nop 0
	s_waitcnt lgkmcnt(7)
	v_mfma_f32_16x16x32_bf16 v[34:37], v[34:37], v[18:21], 0
	s_waitcnt lgkmcnt(6)
	v_mfma_f32_16x16x32_bf16 v[34:37], v[38:41], v[22:25], v[34:37]
	s_waitcnt lgkmcnt(5)
	v_mfma_f32_16x16x32_bf16 v[34:37], v[42:45], v[26:29], v[34:37]
	s_waitcnt lgkmcnt(4)
	v_mfma_f32_16x16x32_bf16 v[34:37], v[62:65], v[30:33], v[34:37]
	s_nop 0
	s_nop 0
	s_waitcnt lgkmcnt(3)
	v_mfma_f32_16x16x32_bf16 v[38:41], v[50:53], v[18:21], 0
	s_waitcnt lgkmcnt(2)
	v_mfma_f32_16x16x32_bf16 v[38:41], v[54:57], v[22:25], v[38:41]
	s_waitcnt lgkmcnt(1)
	v_mfma_f32_16x16x32_bf16 v[38:41], v[58:61], v[26:29], v[38:41]
	s_waitcnt lgkmcnt(0)
; DI float ex2(float x) { return __builtin_amdgcn_exp2f(x); }
; DI void nsa_item(const Params& p, int b, int g, int qb, char* smem, int tid) {
;     ...
;     float tmax = -1e30f;
; #pragma unroll
;     for (int kt = 0; kt < 4; ++kt)
; #pragma unroll
;       for (int i = 0; i < 4; ++i) {
;         int cc = j * 64 + kt * 16 + quad * 4 + i;
;         float v = (cc <= cmax) ? s[kt][i] * SCL : -1e30f;
;         s[kt][i] = v; tmax = fmaxf(tmax, v);
;       }
;     tmax = rowmax4(tmax);
;     float mnew = fmaxf(mx, tmax), rs = 0.f;
; #pragma unroll
;     for (int kt = 0; kt < 4; ++kt)
; #pragma unroll
;       for (int i = 0; i < 4; ++i) { float v = s[kt][i]; rs += (v > -1e29f) ? ex2(v - mnew) : 0.f; }
;     ls = ls * ex2(mx - mnew) + rs; mx = mnew;
	v_mfma_f32_16x16x32_bf16 v[38:41], v[66:69], v[30:33], v[38:41]
	s_nop 0
	v_lshl_or_b32 v14, s12, 6, v214
	v_mul_f32_e32 v10, 0x3e0293ee, v10
	v_cmp_le_i32_e32 vcc, v14, v78
	v_mul_f32_e32 v11, 0x3e0293ee, v11
	v_or_b32_e32 v15, 2, v14
	v_cndmask_b32_e32 v10, v231, v10, vcc
	v_cmp_lt_i32_e32 vcc, v14, v78
	v_mul_f32_e32 v12, 0x3e0293ee, v12
	v_mul_f32_e32 v13, 0x3e0293ee, v13
	v_cndmask_b32_e32 v11, v231, v11, vcc
	v_cmp_le_i32_e32 vcc, v15, v78
	v_or_b32_e32 v15, 3, v14
	v_mul_f32_e32 v42, 0x3e0293ee, v46
	v_cndmask_b32_e32 v12, v231, v12, vcc
	v_cmp_le_i32_e32 vcc, v15, v78
	v_or_b32_e32 v15, 16, v14
	v_mul_f32_e32 v43, 0x3e0293ee, v47
	v_cndmask_b32_e32 v13, v231, v13, vcc
	v_cmp_le_i32_e32 vcc, v15, v78
	v_mul_f32_e32 v44, 0x3e0293ee, v48
	v_mul_f32_e32 v45, 0x3e0293ee, v49
	v_cndmask_b32_e32 v15, v231, v42, vcc
	v_or_b32_e32 v42, 17, v14
	v_cmp_le_i32_e32 vcc, v42, v78
	v_mul_f32_e32 v34, 0x3e0293ee, v34
	v_mul_f32_e32 v35, 0x3e0293ee, v35
	v_cndmask_b32_e32 v42, v231, v43, vcc
	v_or_b32_e32 v43, 18, v14
	v_cmp_le_i32_e32 vcc, v43, v78
	v_mul_f32_e32 v36, 0x3e0293ee, v36
	v_mul_f32_e32 v37, 0x3e0293ee, v37
	v_cndmask_b32_e32 v43, v231, v44, vcc
	v_or_b32_e32 v44, 19, v14
	v_cmp_le_i32_e32 vcc, v44, v78
	v_mul_f32_e32 v38, 0x3e0293ee, v38
	v_mul_f32_e32 v39, 0x3e0293ee, v39
	v_cndmask_b32_e32 v44, v231, v45, vcc
	v_or_b32_e32 v45, 32, v14
	v_cmp_le_i32_e32 vcc, v45, v78
	v_or_b32_e32 v45, 33, v14
	v_mul_f32_e32 v40, 0x3e0293ee, v40
	v_cndmask_b32_e32 v34, v231, v34, vcc
	v_cmp_le_i32_e32 vcc, v45, v78
	v_or_b32_e32 v45, 34, v14
	v_mul_f32_e32 v41, 0x3e0293ee, v41
	v_cndmask_b32_e32 v35, v231, v35, vcc
	v_cmp_le_i32_e32 vcc, v45, v78
	v_or_b32_e32 v45, 35, v14
	s_nop 0
	v_cndmask_b32_e32 v36, v231, v36, vcc
	v_cmp_le_i32_e32 vcc, v45, v78
	v_or_b32_e32 v45, 48, v14
	s_nop 0
	v_cndmask_b32_e32 v37, v231, v37, vcc
	v_cmp_le_i32_e32 vcc, v45, v78
	v_or_b32_e32 v45, 49, v14
	s_nop 0
	v_cndmask_b32_e32 v38, v231, v38, vcc
	v_cmp_le_i32_e32 vcc, v45, v78
	v_or_b32_e32 v45, 50, v14
	v_or_b32_e32 v14, 51, v14
	v_cndmask_b32_e32 v39, v231, v39, vcc
	v_cmp_le_i32_e32 vcc, v45, v78
	s_nop 1
	v_cndmask_b32_e32 v40, v231, v40, vcc
	v_cmp_le_i32_e32 vcc, v14, v78
	s_nop 1
	v_cndmask_b32_e32 v14, v231, v41, vcc
	v_max3_f32 v41, v10, s41, v11
	v_max3_f32 v41, v41, v12, v13
	v_max3_f32 v41, v41, v15, v42
	v_max3_f32 v41, v41, v43, v44
	v_max3_f32 v41, v41, v34, v35
	v_max3_f32 v41, v41, v36, v37
	v_max3_f32 v41, v41, v38, v39
	v_max3_f32 v41, v41, v40, v14
	v_mov_b32_e32 v45, v41
	s_nop 1
	v_permlane16_swap_b32_e32 v41, v45
	v_max_f32_e32 v45, v45, v45
	v_max_f32_e32 v41, v41, v41
	v_max_f32_e32 v41, v41, v45
	v_mov_b32_e32 v45, v41
	s_nop 1
	v_permlane32_swap_b32_e32 v41, v45
	v_max3_f32 v41, v94, v41, v45
	v_sub_f32_e32 v45, v10, v41
	v_exp_f32_e32 v45, v45
	v_cmp_lt_f32_e32 vcc, s33, v10
	v_sub_f32_e32 v46, v12, v41
	v_exp_f32_e32 v46, v46
	v_add_f32_e32 v45, 0, v45
	v_cndmask_b32_e32 v10, 0, v45, vcc
	v_sub_f32_e32 v45, v11, v41
	v_exp_f32_e32 v45, v45
	v_cmp_lt_f32_e32 vcc, s33, v11
	s_nop 1
	v_cndmask_b32_e32 v11, 0, v45, vcc
	v_cmp_lt_f32_e32 vcc, s33, v12
	v_add_f32_e32 v10, v11, v10
	v_sub_f32_e32 v12, v15, v41
	v_cndmask_b32_e32 v11, 0, v46, vcc
	v_add_f32_e32 v10, v11, v10
	v_sub_f32_e32 v11, v13, v41
	v_exp_f32_e32 v11, v11
	v_exp_f32_e32 v12, v12
	v_cmp_lt_f32_e32 vcc, s33, v13
	s_nop 1
	v_cndmask_b32_e32 v11, 0, v11, vcc
	v_cmp_lt_f32_e32 vcc, s33, v15
	v_add_f32_e32 v10, v11, v10
	s_nop 0
	v_cndmask_b32_e32 v11, 0, v12, vcc
	v_add_f32_e32 v10, v11, v10
	v_sub_f32_e32 v11, v42, v41
	v_exp_f32_e32 v11, v11
	v_sub_f32_e32 v12, v43, v41
	v_exp_f32_e32 v12, v12
	v_cmp_lt_f32_e32 vcc, s33, v42
	s_nop 1
	v_cndmask_b32_e32 v11, 0, v11, vcc
	v_cmp_lt_f32_e32 vcc, s33, v43
	v_add_f32_e32 v10, v11, v10
	s_nop 0
	v_cndmask_b32_e32 v11, 0, v12, vcc
	v_add_f32_e32 v10, v11, v10
	v_sub_f32_e32 v11, v44, v41
	v_exp_f32_e32 v11, v11
	v_sub_f32_e32 v12, v34, v41
	v_exp_f32_e32 v12, v12
	v_cmp_lt_f32_e32 vcc, s33, v44
	s_nop 1
	v_cndmask_b32_e32 v11, 0, v11, vcc
	v_cmp_lt_f32_e32 vcc, s33, v34
	v_add_f32_e32 v10, v11, v10
	s_nop 0
	v_cndmask_b32_e32 v11, 0, v12, vcc
	v_add_f32_e32 v10, v11, v10
	v_sub_f32_e32 v11, v35, v41
	v_exp_f32_e32 v11, v11
	v_sub_f32_e32 v12, v36, v41
	v_exp_f32_e32 v12, v12
	v_cmp_lt_f32_e32 vcc, s33, v35
	s_nop 1
	v_cndmask_b32_e32 v11, 0, v11, vcc
	v_cmp_lt_f32_e32 vcc, s33, v36
	v_add_f32_e32 v10, v11, v10
	s_nop 0
	v_cndmask_b32_e32 v11, 0, v12, vcc
	v_add_f32_e32 v10, v11, v10
	v_sub_f32_e32 v11, v37, v41
	v_exp_f32_e32 v11, v11
	v_sub_f32_e32 v12, v38, v41
	v_exp_f32_e32 v12, v12
	v_cmp_lt_f32_e32 vcc, s33, v37
	s_nop 1
	v_cndmask_b32_e32 v11, 0, v11, vcc
	v_cmp_lt_f32_e32 vcc, s33, v38
	v_add_f32_e32 v10, v11, v10
	s_nop 0
	v_cndmask_b32_e32 v11, 0, v12, vcc
	v_add_f32_e32 v10, v11, v10
	v_sub_f32_e32 v11, v39, v41
	v_exp_f32_e32 v11, v11
	v_sub_f32_e32 v12, v40, v41
	v_exp_f32_e32 v12, v12
	v_cmp_lt_f32_e32 vcc, s33, v39
	s_nop 1
	v_cndmask_b32_e32 v11, 0, v11, vcc
	v_cmp_lt_f32_e32 vcc, s33, v40
	v_add_f32_e32 v10, v11, v10
	s_nop 0
	v_cndmask_b32_e32 v11, 0, v12, vcc
	v_add_f32_e32 v10, v11, v10
	v_sub_f32_e32 v11, v14, v41
	v_exp_f32_e32 v11, v11
	v_sub_f32_e32 v12, v94, v41
	v_exp_f32_e32 v12, v12
	v_cmp_lt_f32_e32 vcc, s33, v14
	v_mov_b32_e32 v94, v41
	s_nop 0
	v_cndmask_b32_e32 v11, 0, v11, vcc
	v_add_f32_e32 v10, v11, v10
	v_fmac_f32_e32 v10, v7, v12
	v_mov_b32_e32 v7, v10
	s_mov_b32 s13, 1
	s_andn2_b64 vcc, exec, s[10:11]
	s_mov_b64 s[10:11], 0
	s_cbranch_vccz .LBB0_755

; DI float ex2(float x) { return __builtin_amdgcn_exp2f(x); }
; #define SB0 __builtin_amdgcn_sched_barrier(0)
; DI void nsa_S(f32x4 (&s)[4], const char* Kb, const char* Vb, const bf16x8 (&qf)[4], bf16x8 (&v0)[4], int lr, int quad) {
;   bf16x8 k0[4], k1[4], k2[4], k3[4];
;   ldk4(k0, Kb, 0, lr, quad); SB0;
;   ldk4(k1, Kb, 1, lr, quad); s[0] = mma4(k0, qf); SB0;
;   ldk4(k2, Kb, 2, lr, quad); s[1] = mma4(k1, qf); SB0;
;   ldk4(k3, Kb, 3, lr, quad); s[2] = mma4(k2, qf); SB0;
;   ldv4(v0, Vb, 0, lr, quad); s[3] = mma4(k3, qf); SB0;
; }
; DI void nsa_item(const Params& p, int b, int g, int qb, char* smem, int tid) {
;     ...
;     float* irow = imp + qi * 132;
; #pragma unroll
;     for (int kt = 0; kt < 4; ++kt) {
;       float a = 0.f;
; #pragma unroll
;       for (int i = 0; i < 4; ++i) {
;         int cc = j * 64 + kt * 16 + quad * 4 + i;
;         float pv = (cc <= cmax) ? ex2(s[kt][i] * SCL - mx) * inv : 0.f;
;         s[kt][i] = pv; a += pv;
;       }
;       if (a != 0.f) {
;         int n1 = j * 16 + kt * 4 + quad;
;         atomicAdd(irow + n1, a);
;         if (s[kt][3] != 0.f) atomicAdd(irow + n1 + 1, s[kt][3]);
;       }
;     }
.LBB0_768:
	s_or_b32 s10, s17, s15
	s_cmp_ge_u32 s10, s14
	s_cbranch_scc1 .LBB0_767
	s_lshl_b32 s11, s17, 15
	s_add_i32 s17, s16, s11
	v_add_u32_e32 v8, s17, v234
	v_add_u32_e32 v104, v8, v235
	v_add_u32_e32 v108, v8, v237
	v_add_u32_e32 v105, v8, v236
	ds_read_b128 v[0:3], v104
	ds_read_b128 v[4:7], v105
	v_add_u32_e32 v112, v8, v238
	ds_read_b128 v[8:11], v108
	ds_read_b128 v[12:15], v112
	ds_read_b128 v[66:69], v104 offset:4096
	ds_read_b128 v[70:73], v105 offset:4096
	ds_read_b128 v[74:77], v108 offset:4096
	ds_read_b128 v[96:99], v112 offset:4096
	s_nop 0
	s_waitcnt lgkmcnt(7)
	v_mfma_f32_16x16x32_bf16 v[0:3], v[0:3], v[18:21], 0
	s_waitcnt lgkmcnt(6)
	v_mfma_f32_16x16x32_bf16 v[0:3], v[4:7], v[22:25], v[0:3]
	s_waitcnt lgkmcnt(5)
	v_mfma_f32_16x16x32_bf16 v[0:3], v[8:11], v[26:29], v[0:3]
	s_waitcnt lgkmcnt(4)
	v_mfma_f32_16x16x32_bf16 v[100:103], v[12:15], v[30:33], v[0:3]
	s_nop 0
	s_nop 5
	ds_read_b128 v[0:3], v104 offset:8192
	ds_read_b128 v[4:7], v105 offset:8192
	ds_read_b128 v[8:11], v108 offset:8192
	ds_read_b128 v[12:15], v112 offset:8192
	s_nop 0
	s_waitcnt lgkmcnt(7)
	v_mfma_f32_16x16x32_bf16 v[66:69], v[66:69], v[18:21], 0
	s_waitcnt lgkmcnt(6)
	v_mfma_f32_16x16x32_bf16 v[66:69], v[70:73], v[22:25], v[66:69]
	s_waitcnt lgkmcnt(5)
	v_mfma_f32_16x16x32_bf16 v[66:69], v[74:77], v[26:29], v[66:69]
	s_waitcnt lgkmcnt(4)
	v_mfma_f32_16x16x32_bf16 v[74:77], v[96:99], v[30:33], v[66:69]
	s_nop 0
	s_nop 5
	ds_read_b128 v[66:69], v104 offset:12288
	ds_read_b128 v[104:107], v105 offset:12288
	ds_read_b128 v[108:111], v108 offset:12288
	ds_read_b128 v[112:115], v112 offset:12288
	s_nop 0
	s_waitcnt lgkmcnt(7)
	v_mfma_f32_16x16x32_bf16 v[0:3], v[0:3], v[18:21], 0
	s_waitcnt lgkmcnt(6)
	v_mfma_f32_16x16x32_bf16 v[0:3], v[4:7], v[22:25], v[0:3]
	s_waitcnt lgkmcnt(5)
	v_mfma_f32_16x16x32_bf16 v[0:3], v[8:11], v[26:29], v[0:3]
	s_waitcnt lgkmcnt(4)
	v_mfma_f32_16x16x32_bf16 v[70:73], v[12:15], v[30:33], v[0:3]
	s_nop 0
	s_nop 5
	v_add_u32_e32 v0, s17, v242
	v_add_u32_e32 v96, v0, v241
	ds_read_b128 v[0:3], v96 offset:16384
	ds_read_b128 v[4:7], v96 offset:18432
	ds_read_b128 v[8:11], v96 offset:20480
	ds_read_b128 v[12:15], v96 offset:22528
	s_nop 0
	s_waitcnt lgkmcnt(7)
	v_mfma_f32_16x16x32_bf16 v[66:69], v[66:69], v[18:21], 0
	s_waitcnt lgkmcnt(6)
	v_mfma_f32_16x16x32_bf16 v[66:69], v[104:107], v[22:25], v[66:69]
	s_waitcnt lgkmcnt(5)
	v_mfma_f32_16x16x32_bf16 v[66:69], v[108:111], v[26:29], v[66:69]
	s_waitcnt lgkmcnt(4)
	v_mfma_f32_16x16x32_bf16 v[66:69], v[112:115], v[30:33], v[66:69]
	s_nop 0
	v_fma_f32 v97, v100, s40, -v94
	v_exp_f32_e32 v97, v97
	v_fma_f32 v98, v101, s40, -v94
	v_exp_f32_e32 v98, v98
	s_lshl_b32 s18, s10, 6
	v_fma_f32 v100, v102, s40, -v94
	v_fma_f32 v101, v103, s40, -v94
	v_or_b32_e32 v99, s18, v214
	v_exp_f32_e32 v100, v100
	v_exp_f32_e32 v101, v101
	v_mul_f32_e32 v97, v86, v97
	v_cmp_le_i32_e32 vcc, v99, v78
	v_mul_f32_e32 v98, v86, v98
	v_or_b32_e32 v103, 3, v99
	v_cndmask_b32_e32 v97, 0, v97, vcc
	v_cmp_lt_i32_e32 vcc, v99, v78
	v_add_f32_e32 v104, 0, v97
	v_pk_mul_f32 v[100:101], v[86:87], v[100:101]
	v_cndmask_b32_e32 v98, 0, v98, vcc
	v_add_f32_e32 v102, v98, v104
	v_or_b32_e32 v104, 2, v99
	v_cmp_le_i32_e32 vcc, v103, v79
	s_lshl_b32 s10, s10, 4
	s_nop 0
	v_cndmask_b32_e32 v99, 0, v101, vcc
	v_cmp_le_i32_e32 vcc, v104, v78
	s_nop 1
	v_cndmask_b32_e32 v100, 0, v100, vcc
	v_add_f32_e32 v101, v100, v102
	v_add_f32_e32 v102, v99, v101
	v_cmp_neq_f32_e32 vcc, 0, v102
	v_lshl_add_u32 v101, s10, 2, v95
	s_and_saveexec_b64 s[10:11], vcc
	s_cbranch_execz .LBB0_772
	s_waitcnt vmcnt(0)
	ds_add_f32 v101, v102
	v_cmp_neq_f32_e32 vcc, 0, v99
	s_and_b64 exec, exec, vcc
	ds_add_f32 v101, v99 offset:4

; DI f32x4 mfma16(bf16x8 a, bf16x8 b, f32x4 c) { return __builtin_amdgcn_mfma_f32_16x16x32_bf16(a, b, c, 0, 0, 0); }
; #define SB0 __builtin_amdgcn_sched_barrier(0)
; DI void nsa_PV(f32x4 (&o)[8], const char* Vb, const bf16x8 (&pf)[2], bf16x8 (&v0)[4], int lr, int quad) {
;   bf16x8 v1[4], v2[4], v3[4];
;   SB0;
;   ldv4(v1, Vb, 1, lr, quad);
;   __builtin_amdgcn_s_setprio(1);
; #pragma unroll
;   for (int i = 0; i < 4; ++i) o[i] = mfma16(v0[i], pf[0], o[i]);
;   __builtin_amdgcn_s_setprio(0);
;   SB0;
;   ldv4(v2, Vb, 2, lr, quad);
;   __builtin_amdgcn_s_setprio(1);
; #pragma unroll
;   for (int i = 0; i < 4; ++i) o[4 + i] = mfma16(v1[i], pf[0], o[4 + i]);
;   __builtin_amdgcn_s_setprio(0);
;   SB0;
;   ldv4(v3, Vb, 3, lr, quad);
;   __builtin_amdgcn_s_setprio(1);
; #pragma unroll
;   for (int i = 0; i < 4; ++i) o[i] = mfma16(v2[i], pf[1], o[i]);
;   __builtin_amdgcn_s_setprio(0);
;   SB0;
;   __builtin_amdgcn_s_setprio(1);
; #pragma unroll
;   for (int i = 0; i < 4; ++i) o[4 + i] = mfma16(v3[i], pf[1], o[4 + i]);
;   __builtin_amdgcn_s_setprio(0);
; }
.LBB0_781:
	s_or_b64 exec, exec, s[10:11]
	s_xor_b64 s[10:11], s[8:9], -1
	v_cvt_pk_bf16_f32 v98, v97, v98
	v_cvt_pk_bf16_f32 v99, v100, v99
	v_cvt_pk_bf16_f32 v100, v74, v75
	v_cvt_pk_bf16_f32 v101, v77, v76
	v_cvt_pk_bf16_f32 v70, v70, v71
	v_cvt_pk_bf16_f32 v71, v73, v72
	v_cvt_pk_bf16_f32 v72, v66, v67
	v_cvt_pk_bf16_f32 v73, v69, v68
	ds_read_b128 v[66:69], v96 offset:24576
	ds_read_b128 v[74:77], v96 offset:26624
	ds_read_b128 v[102:105], v96 offset:28672
	ds_read_b128 v[106:109], v96 offset:30720
	s_nop 0
	s_waitcnt lgkmcnt(4)
	v_mfma_f32_16x16x32_bf16 v[0:3], v[0:3], v[98:101], v[62:65]
	v_mfma_f32_16x16x32_bf16 v[4:7], v[4:7], v[98:101], v[58:61]
	v_mfma_f32_16x16x32_bf16 v[8:11], v[8:11], v[98:101], v[54:57]
	v_mfma_f32_16x16x32_bf16 v[12:15], v[12:15], v[98:101], v[50:53]
	s_nop 0
	v_add3_u32 v58, s17, v243, v241
	s_nop 0
	ds_read_b128 v[50:53], v58 offset:16384
	ds_read_b128 v[54:57], v58 offset:18432
	ds_read_b128 v[110:113], v58 offset:20480
	ds_read_b128 v[114:117], v58 offset:22528
	s_nop 0
	s_waitcnt lgkmcnt(7)
	v_mfma_f32_16x16x32_bf16 v[46:49], v[66:69], v[98:101], v[46:49]
	s_waitcnt lgkmcnt(6)
	v_mfma_f32_16x16x32_bf16 v[42:45], v[74:77], v[98:101], v[42:45]
	s_waitcnt lgkmcnt(5)
	v_mfma_f32_16x16x32_bf16 v[38:41], v[102:105], v[98:101], v[38:41]
	s_waitcnt lgkmcnt(4)
	v_mfma_f32_16x16x32_bf16 v[34:37], v[106:109], v[98:101], v[34:37]
	s_nop 0
	ds_read_b128 v[66:69], v58 offset:24576
	ds_read_b128 v[74:77], v58 offset:26624
	ds_read_b128 v[96:99], v58 offset:28672
	ds_read_b128 v[100:103], v58 offset:30720
	s_nop 0
	s_waitcnt lgkmcnt(7)
	v_mfma_f32_16x16x32_bf16 v[62:65], v[50:53], v[70:73], v[0:3]
	s_waitcnt lgkmcnt(6)
	v_mfma_f32_16x16x32_bf16 v[58:61], v[54:57], v[70:73], v[4:7]
	s_waitcnt lgkmcnt(5)
	v_mfma_f32_16x16x32_bf16 v[54:57], v[110:113], v[70:73], v[8:11]
	s_waitcnt lgkmcnt(4)
	v_mfma_f32_16x16x32_bf16 v[50:53], v[114:117], v[70:73], v[12:15]
	s_nop 0
	s_nop 0
	s_waitcnt lgkmcnt(3)
	v_mfma_f32_16x16x32_bf16 v[46:49], v[66:69], v[70:73], v[46:49]
	s_waitcnt lgkmcnt(2)
	v_mfma_f32_16x16x32_bf16 v[42:45], v[74:77], v[70:73], v[42:45]
	s_waitcnt lgkmcnt(1)
	v_mfma_f32_16x16x32_bf16 v[38:41], v[96:99], v[70:73], v[38:41]
	s_waitcnt lgkmcnt(0)
	v_mfma_f32_16x16x32_bf16 v[34:37], v[100:103], v[70:73], v[34:37]
	s_nop 0
	s_mov_b32 s17, 1
	s_mov_b64 s[8:9], 0
	s_and_b64 vcc, exec, s[10:11]
	s_cbranch_vccz .LBB0_768

; #define SB0 __builtin_amdgcn_sched_barrier(0)
; DI void nsa_S(f32x4 (&s)[4], const char* Kb, const char* Vb, const bf16x8 (&qf)[4], bf16x8 (&v0)[4], int lr, int quad) {
;   bf16x8 k0[4], k1[4], k2[4], k3[4];
;   ldk4(k0, Kb, 0, lr, quad); SB0;
;   ldk4(k1, Kb, 1, lr, quad); s[0] = mma4(k0, qf); SB0;
;   ldk4(k2, Kb, 2, lr, quad); s[1] = mma4(k1, qf); SB0;
;   ldk4(k3, Kb, 3, lr, quad); s[2] = mma4(k2, qf); SB0;
;   ldv4(v0, Vb, 0, lr, quad); s[3] = mma4(k3, qf); SB0;
; }
; DI void nsa_item(const Params& p, int b, int g, int qb, char* smem, int tid) {
;     ...
;       const bool sb = (sel[qi * 4 + (j >> 5)] >> (j & 31)) & 1u;
;       if (!__any(sb)) return;
;       f32x4 s[4];
;       bf16x8 va[4];
;       nsa_S(s, Kb, Vb, qf, va, lr, quad);
;       auto mf = [&](int kt, int i) __attribute__((always_inline)) { return j * 64 + kt * 16 + quad * 4 + i > qp; };
;       if (j == cur) flash_update<true>(s, SCL, mx2, l2, o, mf, sb);
;       else flash_update<false>(s, SCL, mx2, l2, o, mf, sb);
.LBB0_817:
	s_or_b32 s59, s48, s56
	s_cmp_gt_u32 s59, s2
	s_cbranch_scc1 .LBB0_816
	s_and_b32 s38, s59, 31
	s_waitcnt lgkmcnt(0)
	v_mov_b32_e32 v0, v172
	v_lshrrev_b32_e32 v1, s59, v0
	v_bfe_u32 v0, v0, s38, 1
	v_and_b32_e32 v1, 1, v1
	v_cmp_ne_u32_e32 vcc, 0, v0
	v_cmp_eq_u32_e64 s[38:39], 1, v1
	s_cbranch_vccz .LBB0_829
	s_lshl_b32 s48, s48, 15
	s_add_i32 s58, s57, s48
	v_add_u32_e32 v8, s58, v234
	v_add_u32_e32 v122, v8, v235
	v_add_u32_e32 v124, v8, v237
	v_add_u32_e32 v123, v8, v236
	ds_read_b128 v[0:3], v122
	ds_read_b128 v[4:7], v123
	v_add_u32_e32 v125, v8, v238
	ds_read_b128 v[8:11], v124
	ds_read_b128 v[12:15], v125
	ds_read_b128 v[98:101], v122 offset:4096
	ds_read_b128 v[102:105], v123 offset:4096
	ds_read_b128 v[106:109], v124 offset:4096
	ds_read_b128 v[110:113], v125 offset:4096
	s_nop 0
	s_waitcnt lgkmcnt(7)
	v_mfma_f32_16x16x32_bf16 v[0:3], v[0:3], v[18:21], 0
	s_waitcnt lgkmcnt(6)
	v_mfma_f32_16x16x32_bf16 v[0:3], v[4:7], v[22:25], v[0:3]
	s_waitcnt lgkmcnt(5)
	v_mfma_f32_16x16x32_bf16 v[0:3], v[8:11], v[26:29], v[0:3]
	s_waitcnt lgkmcnt(4)
	v_mfma_f32_16x16x32_bf16 v[114:117], v[12:15], v[30:33], v[0:3]
	s_nop 0
	s_nop 5
	ds_read_b128 v[0:3], v122 offset:8192
	ds_read_b128 v[4:7], v123 offset:8192
	ds_read_b128 v[8:11], v124 offset:8192
	ds_read_b128 v[12:15], v125 offset:8192
	s_nop 0
	s_waitcnt lgkmcnt(7)
	v_mfma_f32_16x16x32_bf16 v[98:101], v[98:101], v[18:21], 0
	s_waitcnt lgkmcnt(6)
	v_mfma_f32_16x16x32_bf16 v[98:101], v[102:105], v[22:25], v[98:101]
	s_waitcnt lgkmcnt(5)
	v_mfma_f32_16x16x32_bf16 v[98:101], v[106:109], v[26:29], v[98:101]
	s_waitcnt lgkmcnt(4)
	v_mfma_f32_16x16x32_bf16 v[118:121], v[110:113], v[30:33], v[98:101]
	s_nop 0
	ds_read_b128 v[126:129], v122 offset:12288
	ds_read_b128 v[130:133], v123 offset:12288
	ds_read_b128 v[134:137], v124 offset:12288
	ds_read_b128 v[138:141], v125 offset:12288
	s_nop 0
	s_waitcnt lgkmcnt(7)
	v_mfma_f32_16x16x32_bf16 v[0:3], v[0:3], v[18:21], 0
	s_waitcnt lgkmcnt(6)
	v_mfma_f32_16x16x32_bf16 v[0:3], v[4:7], v[22:25], v[0:3]
	s_waitcnt lgkmcnt(5)
	v_mfma_f32_16x16x32_bf16 v[0:3], v[8:11], v[26:29], v[0:3]
	s_waitcnt lgkmcnt(4)
	v_mfma_f32_16x16x32_bf16 v[122:125], v[12:15], v[30:33], v[0:3]
	s_nop 0
	s_nop 5
	v_add_u32_e32 v0, s58, v242
	v_add_u32_e32 v174, v0, v241
	ds_read_b128 v[98:101], v174 offset:16384
	ds_read_b128 v[102:105], v174 offset:18432
	ds_read_b128 v[106:109], v174 offset:20480
	ds_read_b128 v[110:113], v174 offset:22528
	s_nop 0
	s_waitcnt lgkmcnt(7)
	v_mfma_f32_16x16x32_bf16 v[0:3], v[126:129], v[18:21], 0
	s_waitcnt lgkmcnt(6)
	v_mfma_f32_16x16x32_bf16 v[0:3], v[130:133], v[22:25], v[0:3]
	s_waitcnt lgkmcnt(5)
	v_mfma_f32_16x16x32_bf16 v[0:3], v[134:137], v[26:29], v[0:3]
	s_waitcnt lgkmcnt(4)
	v_mfma_f32_16x16x32_bf16 v[126:129], v[138:141], v[30:33], v[0:3]
	s_nop 0
	s_mov_b64 s[48:49], -1
	s_cmp_lg_u32 s59, s2
	v_add_f32_e32 v176, 0x427af232, v173
	s_cbranch_scc0 .LBB0_823
	s_nop 1
	v_max3_f32 v0, v114, s41, v115
	v_max3_f32 v0, v0, v116, v117
	v_max3_f32 v0, v0, v118, v119
	v_max3_f32 v0, v0, v120, v121
	v_max3_f32 v0, v0, v122, v123
	v_max3_f32 v0, v0, v124, v125
	v_max3_f32 v0, v0, v126, v127
	v_max3_f32 v0, v0, v128, v129
	v_mov_b32_e32 v1, v0
	s_nop 1
	v_permlane16_swap_b32_e32 v0, v1
	v_max_f32_e32 v1, v1, v1
	v_max_f32_e32 v0, v0, v0
	v_max_f32_e32 v0, v0, v1
	v_mov_b32_e32 v1, v0
	s_nop 1
	v_permlane32_swap_b32_e32 v0, v1
	v_max_f32_e32 v1, v1, v1
	v_max_f32_e32 v0, v0, v0
	v_max_f32_e32 v0, v0, v1
	v_cndmask_b32_e64 v0, v231, v0, s[38:39]
	v_mov_b64_e32 v[160:161], v[68:69]
	v_mov_b64_e32 v[156:157], v[72:73]
	v_mov_b64_e32 v[152:153], v[76:77]
	v_mov_b64_e32 v[148:149], v[80:81]
	v_mov_b64_e32 v[144:145], v[84:85]
	v_mov_b64_e32 v[140:141], v[88:89]
	v_mov_b64_e32 v[136:137], v[92:93]
	v_mov_b64_e32 v[132:133], v[96:97]
	v_cmp_gt_f32_e32 vcc, v0, v176
	v_mov_b64_e32 v[158:159], v[66:67]
	v_mov_b64_e32 v[154:155], v[70:71]
	v_mov_b64_e32 v[150:151], v[74:75]
	v_mov_b64_e32 v[146:147], v[78:79]
	v_mov_b64_e32 v[142:143], v[82:83]
	v_mov_b64_e32 v[138:139], v[86:87]
	v_mov_b64_e32 v[134:135], v[90:91]
	v_mov_b64_e32 v[130:131], v[94:95]
	v_mov_b32_e32 v177, v170
	v_mov_b32_e32 v175, v173
	s_cbranch_vccz .LBB0_822
	v_max_f32_e32 v0, v0, v0
	v_max_f32_e32 v1, v173, v173
	v_max_f32_e32 v175, v1, v0
	v_sub_f32_e32 v0, v173, v175
	v_mul_f32_e32 v0, 0x3e0293ee, v0
	v_exp_f32_e32 v0, v0
	s_nop 0
	v_mul_f32_e32 v177, v170, v0
	v_pk_mul_f32 v[132:133], v[96:97], v[0:1] op_sel_hi:[1,0]
	v_pk_mul_f32 v[130:131], v[94:95], v[0:1] op_sel_hi:[1,0]
	v_pk_mul_f32 v[136:137], v[92:93], v[0:1] op_sel_hi:[1,0]
	v_pk_mul_f32 v[134:135], v[90:91], v[0:1] op_sel_hi:[1,0]
	v_pk_mul_f32 v[140:141], v[88:89], v[0:1] op_sel_hi:[1,0]
	v_pk_mul_f32 v[138:139], v[86:87], v[0:1] op_sel_hi:[1,0]
	v_pk_mul_f32 v[144:145], v[84:85], v[0:1] op_sel_hi:[1,0]
	v_pk_mul_f32 v[142:143], v[82:83], v[0:1] op_sel_hi:[1,0]
	v_pk_mul_f32 v[148:149], v[80:81], v[0:1] op_sel_hi:[1,0]
	v_pk_mul_f32 v[146:147], v[78:79], v[0:1] op_sel_hi:[1,0]
	v_pk_mul_f32 v[152:153], v[76:77], v[0:1] op_sel_hi:[1,0]
	v_pk_mul_f32 v[150:151], v[74:75], v[0:1] op_sel_hi:[1,0]
	v_pk_mul_f32 v[156:157], v[72:73], v[0:1] op_sel_hi:[1,0]
	v_pk_mul_f32 v[154:155], v[70:71], v[0:1] op_sel_hi:[1,0]
	v_pk_mul_f32 v[160:161], v[68:69], v[0:1] op_sel_hi:[1,0]
	v_pk_mul_f32 v[158:159], v[66:67], v[0:1] op_sel_hi:[1,0]

; DI f32x4 mfma16(bf16x8 a, bf16x8 b, f32x4 c) { return __builtin_amdgcn_mfma_f32_16x16x32_bf16(a, b, c, 0, 0, 0); }
; #define SB0 __builtin_amdgcn_sched_barrier(0)
; DI void nsa_PV(f32x4 (&o)[8], const char* Vb, const bf16x8 (&pf)[2], bf16x8 (&v0)[4], int lr, int quad) {
;   bf16x8 v1[4], v2[4], v3[4];
;   SB0;
;   ldv4(v1, Vb, 1, lr, quad);
;   __builtin_amdgcn_s_setprio(1);
; #pragma unroll
;   for (int i = 0; i < 4; ++i) o[i] = mfma16(v0[i], pf[0], o[i]);
;   __builtin_amdgcn_s_setprio(0);
;   SB0;
;   ldv4(v2, Vb, 2, lr, quad);
;   __builtin_amdgcn_s_setprio(1);
; #pragma unroll
;   for (int i = 0; i < 4; ++i) o[4 + i] = mfma16(v1[i], pf[0], o[4 + i]);
;   __builtin_amdgcn_s_setprio(0);
;   SB0;
;   ldv4(v3, Vb, 3, lr, quad);
;   __builtin_amdgcn_s_setprio(1);
; #pragma unroll
;   for (int i = 0; i < 4; ++i) o[i] = mfma16(v2[i], pf[1], o[i]);
;   __builtin_amdgcn_s_setprio(0);
;   SB0;
;   __builtin_amdgcn_s_setprio(1);
; #pragma unroll
;   for (int i = 0; i < 4; ++i) o[4 + i] = mfma16(v3[i], pf[1], o[4 + i]);
;   __builtin_amdgcn_s_setprio(0);
; }
.LBB0_828:
	v_add_f32_e32 v170, v177, v178
	v_cvt_pk_bf16_f32 v0, v0, v1
	v_cvt_pk_bf16_f32 v1, v2, v3
	v_cvt_pk_bf16_f32 v2, v4, v5
	v_cvt_pk_bf16_f32 v3, v6, v7
	v_cvt_pk_bf16_f32 v4, v8, v9
	v_cvt_pk_bf16_f32 v5, v10, v11
	v_cvt_pk_bf16_f32 v6, v12, v13
	v_cvt_pk_bf16_f32 v7, v14, v15
	ds_read_b128 v[8:11], v174 offset:24576
	ds_read_b128 v[12:15], v174 offset:26624
	ds_read_b128 v[66:69], v174 offset:28672
	ds_read_b128 v[70:73], v174 offset:30720
	s_nop 0
	s_waitcnt lgkmcnt(4)
	v_mfma_f32_16x16x32_bf16 v[74:77], v[98:101], v[0:3], v[130:133]
	v_mfma_f32_16x16x32_bf16 v[78:81], v[102:105], v[0:3], v[134:137]
	v_mfma_f32_16x16x32_bf16 v[82:85], v[106:109], v[0:3], v[138:141]
	v_mfma_f32_16x16x32_bf16 v[98:101], v[110:113], v[0:3], v[142:145]
	s_nop 0
	v_add3_u32 v94, s58, v243, v241
	ds_read_b128 v[86:89], v94 offset:16384
	ds_read_b128 v[90:93], v94 offset:18432
	ds_read_b128 v[102:105], v94 offset:20480
	ds_read_b128 v[106:109], v94 offset:22528
	s_nop 0
	s_waitcnt lgkmcnt(5)
	v_mfma_f32_16x16x32_bf16 v[66:69], v[66:69], v[0:3], v[154:157]
	v_mfma_f32_16x16x32_bf16 v[8:11], v[8:11], v[0:3], v[146:149]
	v_mfma_f32_16x16x32_bf16 v[12:15], v[12:15], v[0:3], v[150:153]
	s_waitcnt lgkmcnt(4)
	v_mfma_f32_16x16x32_bf16 v[0:3], v[70:73], v[0:3], v[158:161]
	s_nop 0
	ds_read_b128 v[70:73], v94 offset:24576
	ds_read_b128 v[110:113], v94 offset:26624
	ds_read_b128 v[114:117], v94 offset:28672
	ds_read_b128 v[118:121], v94 offset:30720
	s_nop 0
	s_waitcnt lgkmcnt(7)
	v_mfma_f32_16x16x32_bf16 v[94:97], v[86:89], v[4:7], v[74:77]
	s_waitcnt lgkmcnt(6)
	v_mfma_f32_16x16x32_bf16 v[90:93], v[90:93], v[4:7], v[78:81]
	s_waitcnt lgkmcnt(5)
	v_mfma_f32_16x16x32_bf16 v[86:89], v[102:105], v[4:7], v[82:85]
	s_waitcnt lgkmcnt(4)
	v_mfma_f32_16x16x32_bf16 v[82:85], v[106:109], v[4:7], v[98:101]
	s_nop 0
	s_nop 0
	s_waitcnt lgkmcnt(3)
	v_mfma_f32_16x16x32_bf16 v[78:81], v[70:73], v[4:7], v[8:11]
	s_waitcnt lgkmcnt(2)
	v_mfma_f32_16x16x32_bf16 v[74:77], v[110:113], v[4:7], v[12:15]
	s_waitcnt lgkmcnt(1)
	v_mfma_f32_16x16x32_bf16 v[70:73], v[114:117], v[4:7], v[66:69]
	s_waitcnt lgkmcnt(0)
	v_mfma_f32_16x16x32_bf16 v[66:69], v[118:121], v[4:7], v[0:3]
	s_nop 0
	v_mov_b32_e32 v173, v175

; #define SB0 __builtin_amdgcn_sched_barrier(0)
; DI void nsa_S(f32x4 (&s)[4], const char* Kb, const char* Vb, const bf16x8 (&qf)[4], bf16x8 (&v0)[4], int lr, int quad) {
;   bf16x8 k0[4], k1[4], k2[4], k3[4];
;   ldk4(k0, Kb, 0, lr, quad); SB0;
;   ldk4(k1, Kb, 1, lr, quad); s[0] = mma4(k0, qf); SB0;
;   ldk4(k2, Kb, 2, lr, quad); s[1] = mma4(k1, qf); SB0;
;   ldk4(k3, Kb, 3, lr, quad); s[2] = mma4(k2, qf); SB0;
;   ldv4(v0, Vb, 0, lr, quad); s[3] = mma4(k3, qf); SB0;
; }
; DI void nsa_item(const Params& p, int b, int g, int qb, char* smem, int tid) {
;     ...
;       nsa_S(s, Kb, Vb, qf, va, lr, quad);
;       auto mf = [&](int kt, int i) __attribute__((always_inline)) {
;         int key = j * 64 + kt * 16 + quad * 4 + i;
;         return (key > qp) || (key <= qp - 512);
;       };
;       if (j * 64 + 63 <= q0 && j * 64 > q0 + 31 - 512) flash_update<false>(s, SCL, mx2, l2, o, mf, true);
;       else flash_update<true>(s, SCL, mx2, l2, o, mf, true);
.LBB0_844:
	s_lshl_b32 s5, s6, 15
	s_add_i32 s24, s23, s5
	v_add_u32_e32 v8, s24, v234
	v_add_u32_e32 v146, v8, v235
	v_add_u32_e32 v151, v8, v237
	v_add_u32_e32 v150, v8, v236
	ds_read_b128 v[0:3], v146
	ds_read_b128 v[4:7], v150
	v_add_u32_e32 v152, v8, v238
	ds_read_b128 v[8:11], v151
	ds_read_b128 v[12:15], v152
	ds_read_b128 v[130:133], v146 offset:4096
	ds_read_b128 v[134:137], v150 offset:4096
	ds_read_b128 v[138:141], v151 offset:4096
	ds_read_b128 v[142:145], v152 offset:4096
	s_nop 0
	s_waitcnt lgkmcnt(7)
	v_mfma_f32_16x16x32_bf16 v[0:3], v[0:3], v[18:21], 0
	s_waitcnt lgkmcnt(6)
	v_mfma_f32_16x16x32_bf16 v[0:3], v[4:7], v[22:25], v[0:3]
	s_waitcnt lgkmcnt(5)
	v_mfma_f32_16x16x32_bf16 v[0:3], v[8:11], v[26:29], v[0:3]
	s_waitcnt lgkmcnt(4)
	v_mfma_f32_16x16x32_bf16 v[158:161], v[12:15], v[30:33], v[0:3]
	s_nop 0
	s_nop 5
	ds_read_b128 v[0:3], v146 offset:8192
	ds_read_b128 v[4:7], v150 offset:8192
	ds_read_b128 v[8:11], v151 offset:8192
	ds_read_b128 v[12:15], v152 offset:8192
	s_nop 0
	s_waitcnt lgkmcnt(7)
	v_mfma_f32_16x16x32_bf16 v[130:133], v[130:133], v[18:21], 0
	s_waitcnt lgkmcnt(6)
	v_mfma_f32_16x16x32_bf16 v[130:133], v[134:137], v[22:25], v[130:133]
	s_waitcnt lgkmcnt(5)
	v_mfma_f32_16x16x32_bf16 v[130:133], v[138:141], v[26:29], v[130:133]
	s_waitcnt lgkmcnt(4)
	v_mfma_f32_16x16x32_bf16 v[154:157], v[142:145], v[30:33], v[130:133]
	s_nop 0
	ds_read_b128 v[146:149], v146 offset:12288
	ds_read_b128 v[162:165], v150 offset:12288
	ds_read_b128 v[166:169], v151 offset:12288
	ds_read_b128 v[170:173], v152 offset:12288
	s_nop 0
	s_waitcnt lgkmcnt(7)
	v_mfma_f32_16x16x32_bf16 v[0:3], v[0:3], v[18:21], 0
	s_waitcnt lgkmcnt(6)
	v_mfma_f32_16x16x32_bf16 v[0:3], v[4:7], v[22:25], v[0:3]
	s_waitcnt lgkmcnt(5)
	v_mfma_f32_16x16x32_bf16 v[0:3], v[8:11], v[26:29], v[0:3]
	s_waitcnt lgkmcnt(4)
	v_mfma_f32_16x16x32_bf16 v[150:153], v[12:15], v[30:33], v[0:3]
	s_nop 0
	s_nop 5
	v_add_u32_e32 v0, s24, v242
	v_add_u32_e32 v247, v0, v241
	ds_read_b128 v[130:133], v247 offset:16384
	ds_read_b128 v[134:137], v247 offset:18432
	ds_read_b128 v[138:141], v247 offset:20480
	ds_read_b128 v[142:145], v247 offset:22528
	s_nop 0
	s_waitcnt lgkmcnt(7)
	v_mfma_f32_16x16x32_bf16 v[0:3], v[146:149], v[18:21], 0
	s_waitcnt lgkmcnt(6)
	v_mfma_f32_16x16x32_bf16 v[0:3], v[162:165], v[22:25], v[0:3]
	s_waitcnt lgkmcnt(5)
	v_mfma_f32_16x16x32_bf16 v[0:3], v[166:169], v[26:29], v[0:3]
	s_waitcnt lgkmcnt(4)
	v_mfma_f32_16x16x32_bf16 v[146:149], v[170:173], v[30:33], v[0:3]
	s_nop 0
	s_lshl_b32 s6, s4, 6
	s_or_b32 s4, s6, 63
	s_cmp_le_u32 s4, s85
	s_cselect_b64 s[4:5], -1, 0
	s_cmp_gt_i32 s6, s21
	s_cselect_b64 s[8:9], -1, 0
	s_and_b64 s[8:9], s[4:5], s[8:9]
	s_mov_b64 s[4:5], -1
	s_andn2_b64 vcc, exec, s[8:9]
	v_add_f32_e32 v249, 0x427af232, v246
	s_cbranch_vccz .LBB0_849
; DI float ex2(float x) { return __builtin_amdgcn_exp2f(x); }
; template <bool MASKED, class MF>
; DI void flash_update(f32x4 (&s)[4], float scl, float& mx, float& ls, f32x4 (&o)[8], MF maskfn, bool lane_on) {
;   float tmax = -1e30f;
; #pragma unroll
;   for (int kt = 0; kt < 4; ++kt)
; #pragma unroll
;     for (int i = 0; i < 4; ++i) {
;       if (MASKED) { if (maskfn(kt, i)) s[kt][i] = -1e30f; }
;       tmax = fmaxf(tmax, s[kt][i]);
;     }
;   tmax = rowmax4(tmax);
;   if (!lane_on) tmax = -1e30f;
;   const float th = 8.f / scl;
;   if (__any(tmax > mx + th)) {
;     const float mnew = fmaxf(mx, tmax);
;     const float alpha = ex2((mx - mnew) * scl);
;     ls *= alpha;
; #pragma unroll
;     for (int dt = 0; dt < 8; ++dt) o[dt] *= alpha;
;     mx = mnew;
;   }
; DI void nsa_item(const Params& p, int b, int g, int qb, char* smem, int tid) {
;     ...
;       auto mf = [&](int kt, int i) __attribute__((always_inline)) {
;         int key = j * 64 + kt * 16 + quad * 4 + i;
;         return (key > qp) || (key <= qp - 512);
;       };
;       if (j * 64 + 63 <= q0 && j * 64 > q0 + 31 - 512) flash_update<false>(s, SCL, mx2, l2, o, mf, true);
;       else flash_update<true>(s, SCL, mx2, l2, o, mf, true);
	v_or_b32_e32 v15, s6, v214
	v_cmp_gt_i32_e32 vcc, v15, v233
	v_cmp_le_i32_e64 s[4:5], v15, v245
	s_or_b64 vcc, vcc, s[4:5]
	v_cndmask_b32_e32 v0, v158, v231, vcc
	v_cmp_ge_i32_e32 vcc, v15, v233
	v_cmp_lt_i32_e64 s[4:5], v15, v245
	s_or_b64 vcc, vcc, s[4:5]
	v_or_b32_e32 v2, 2, v15
	v_cndmask_b32_e32 v1, v159, v231, vcc
	v_cmp_gt_i32_e32 vcc, v2, v233
	v_cmp_le_i32_e64 s[4:5], v2, v245
	s_or_b64 vcc, vcc, s[4:5]
	v_or_b32_e32 v3, 3, v15
	v_cndmask_b32_e32 v2, v160, v231, vcc
	v_cmp_gt_i32_e32 vcc, v3, v233
	v_cmp_le_i32_e64 s[4:5], v3, v245
	s_or_b64 s[4:5], vcc, s[4:5]
	v_max3_f32 v4, v0, s41, v1
	v_cndmask_b32_e64 v3, v161, v231, s[4:5]
	v_max3_f32 v6, v4, v2, v3
	v_or_b32_e32 v4, 16, v15
	v_cmp_gt_i32_e32 vcc, v4, v233
	v_cmp_le_i32_e64 s[6:7], v4, v245
	s_or_b64 vcc, vcc, s[6:7]
	v_or_b32_e32 v5, 17, v15
	v_cndmask_b32_e32 v4, v154, v231, vcc
	v_cmp_gt_i32_e32 vcc, v5, v233
	v_cmp_le_i32_e64 s[6:7], v5, v245
	s_or_b64 vcc, vcc, s[6:7]
	v_cndmask_b32_e32 v5, v155, v231, vcc
	v_max3_f32 v8, v6, v4, v5
	v_or_b32_e32 v6, 18, v15
	v_cmp_gt_i32_e32 vcc, v6, v233
	v_cmp_le_i32_e64 s[6:7], v6, v245
	s_or_b64 vcc, vcc, s[6:7]
	v_or_b32_e32 v7, 19, v15
	v_cndmask_b32_e32 v6, v156, v231, vcc
	v_cmp_gt_i32_e32 vcc, v7, v233
	v_cmp_le_i32_e64 s[6:7], v7, v245
	s_or_b64 s[6:7], vcc, s[6:7]
	v_or_b32_e32 v9, 33, v15
	v_cndmask_b32_e64 v7, v157, v231, s[6:7]
	v_max3_f32 v10, v8, v6, v7
	v_or_b32_e32 v8, 32, v15
	v_cmp_gt_i32_e32 vcc, v8, v233
	v_cmp_le_i32_e64 s[8:9], v8, v245
	s_or_b64 vcc, vcc, s[8:9]
	v_cndmask_b32_e32 v8, v150, v231, vcc
	v_cmp_gt_i32_e32 vcc, v9, v233
	v_cmp_le_i32_e64 s[8:9], v9, v245
	s_or_b64 vcc, vcc, s[8:9]
	v_cndmask_b32_e32 v9, v151, v231, vcc
	v_max3_f32 v12, v10, v8, v9
	v_or_b32_e32 v10, 34, v15
	v_cmp_gt_i32_e32 vcc, v10, v233
	v_cmp_le_i32_e64 s[8:9], v10, v245
	s_or_b64 vcc, vcc, s[8:9]
	v_or_b32_e32 v11, 35, v15
	v_cndmask_b32_e32 v10, v152, v231, vcc
	v_cmp_gt_i32_e32 vcc, v11, v233
	v_cmp_le_i32_e64 s[8:9], v11, v245
	s_or_b64 s[8:9], vcc, s[8:9]
	v_or_b32_e32 v13, 49, v15
	v_cndmask_b32_e64 v11, v153, v231, s[8:9]
	v_max3_f32 v14, v12, v10, v11
	v_or_b32_e32 v12, 48, v15
	v_cmp_gt_i32_e32 vcc, v12, v233
	v_cmp_le_i32_e64 s[10:11], v12, v245
	s_or_b64 vcc, vcc, s[10:11]
	v_cndmask_b32_e32 v12, v146, v231, vcc
	v_cmp_gt_i32_e32 vcc, v13, v233
	v_cmp_le_i32_e64 s[10:11], v13, v245
	s_or_b64 vcc, vcc, s[10:11]
	v_cndmask_b32_e32 v13, v147, v231, vcc
	v_max3_f32 v162, v14, v12, v13
	v_or_b32_e32 v14, 50, v15
	v_cmp_gt_i32_e32 vcc, v14, v233
	v_cmp_le_i32_e64 s[10:11], v14, v245
	s_or_b64 vcc, vcc, s[10:11]
	v_or_b32_e32 v15, 51, v15
	v_cndmask_b32_e32 v14, v148, v231, vcc
	v_cmp_gt_i32_e32 vcc, v15, v233
	v_cmp_le_i32_e64 s[10:11], v15, v245
	s_or_b64 s[10:11], vcc, s[10:11]
	s_nop 0
	v_cndmask_b32_e64 v15, v149, v231, s[10:11]
	v_max3_f32 v162, v162, v14, v15
	v_mov_b32_e32 v163, v162
	s_nop 1
	v_permlane16_swap_b32_e32 v162, v163
	v_max_f32_e32 v163, v163, v163
	v_max_f32_e32 v162, v162, v162
	v_max_f32_e32 v162, v162, v163
	v_mov_b32_e32 v163, v162
	s_nop 1
	v_permlane32_swap_b32_e32 v162, v163
	v_max_f32_e32 v163, v163, v163
	v_max_f32_e32 v162, v162, v162
	v_max_f32_e32 v162, v162, v163
	v_cmp_gt_f32_e32 vcc, v162, v249
	s_cbranch_vccz .LBB0_847
	v_max_f32_e32 v7, v162, v162
	v_max_f32_e32 v11, v246, v246
	v_max_f32_e32 v248, v11, v7
	v_sub_f32_e32 v7, v246, v248
	v_mul_f32_e32 v7, 0x3e0293ee, v7
	v_exp_f32_e32 v190, v7
	v_cndmask_b32_e64 v3, v161, v231, s[4:5]
	v_cndmask_b32_e64 v7, v157, v231, s[6:7]
	v_cndmask_b32_e64 v11, v153, v231, s[8:9]
	v_cndmask_b32_e64 v15, v149, v231, s[10:11]
	v_mul_f32_e32 v250, v244, v190
	v_pk_mul_f32 v[164:165], v[128:129], v[190:191] op_sel_hi:[1,0]
	v_pk_mul_f32 v[162:163], v[126:127], v[190:191] op_sel_hi:[1,0]
	v_pk_mul_f32 v[168:169], v[124:125], v[190:191] op_sel_hi:[1,0]
	v_pk_mul_f32 v[166:167], v[122:123], v[190:191] op_sel_hi:[1,0]
	v_pk_mul_f32 v[172:173], v[120:121], v[190:191] op_sel_hi:[1,0]
	v_pk_mul_f32 v[170:171], v[118:119], v[190:191] op_sel_hi:[1,0]
	v_pk_mul_f32 v[176:177], v[116:117], v[190:191] op_sel_hi:[1,0]
	v_pk_mul_f32 v[174:175], v[114:115], v[190:191] op_sel_hi:[1,0]
	v_pk_mul_f32 v[180:181], v[112:113], v[190:191] op_sel_hi:[1,0]
	v_pk_mul_f32 v[178:179], v[110:111], v[190:191] op_sel_hi:[1,0]
	v_pk_mul_f32 v[184:185], v[108:109], v[190:191] op_sel_hi:[1,0]
	v_pk_mul_f32 v[182:183], v[106:107], v[190:191] op_sel_hi:[1,0]
	v_pk_mul_f32 v[188:189], v[104:105], v[190:191] op_sel_hi:[1,0]
	v_pk_mul_f32 v[186:187], v[102:103], v[190:191] op_sel_hi:[1,0]
	v_pk_mul_f32 v[192:193], v[100:101], v[190:191] op_sel_hi:[1,0]
	v_pk_mul_f32 v[190:191], v[98:99], v[190:191] op_sel_hi:[1,0]
	s_branch .LBB0_848

; DI f32x4 mfma16(bf16x8 a, bf16x8 b, f32x4 c) { return __builtin_amdgcn_mfma_f32_16x16x32_bf16(a, b, c, 0, 0, 0); }
; #define SB0 __builtin_amdgcn_sched_barrier(0)
; DI void nsa_PV(f32x4 (&o)[8], const char* Vb, const bf16x8 (&pf)[2], bf16x8 (&v0)[4], int lr, int quad) {
;   bf16x8 v1[4], v2[4], v3[4];
;   SB0;
;   ldv4(v1, Vb, 1, lr, quad);
;   __builtin_amdgcn_s_setprio(1);
; #pragma unroll
;   for (int i = 0; i < 4; ++i) o[i] = mfma16(v0[i], pf[0], o[i]);
;   __builtin_amdgcn_s_setprio(0);
;   SB0;
;   ldv4(v2, Vb, 2, lr, quad);
;   __builtin_amdgcn_s_setprio(1);
; #pragma unroll
;   for (int i = 0; i < 4; ++i) o[4 + i] = mfma16(v1[i], pf[0], o[4 + i]);
;   __builtin_amdgcn_s_setprio(0);
;   SB0;
;   ldv4(v3, Vb, 3, lr, quad);
;   __builtin_amdgcn_s_setprio(1);
; #pragma unroll
;   for (int i = 0; i < 4; ++i) o[i] = mfma16(v2[i], pf[1], o[i]);
;   __builtin_amdgcn_s_setprio(0);
;   SB0;
;   __builtin_amdgcn_s_setprio(1);
; #pragma unroll
;   for (int i = 0; i < 4; ++i) o[4 + i] = mfma16(v3[i], pf[1], o[4 + i]);
;   __builtin_amdgcn_s_setprio(0);
; }
.LBB0_853:
	s_xor_b64 s[4:5], s[14:15], -1
	v_add_f32_e32 v244, v250, v251
	v_cvt_pk_bf16_f32 v0, v0, v1
	v_cvt_pk_bf16_f32 v1, v2, v3
	v_cvt_pk_bf16_f32 v2, v4, v5
	v_cvt_pk_bf16_f32 v3, v6, v7
	v_cvt_pk_bf16_f32 v4, v8, v9
	v_cvt_pk_bf16_f32 v5, v10, v11
	v_cvt_pk_bf16_f32 v6, v12, v13
	v_cvt_pk_bf16_f32 v7, v14, v15
	ds_read_b128 v[8:11], v247 offset:24576
	ds_read_b128 v[12:15], v247 offset:26624
	ds_read_b128 v[98:101], v247 offset:28672
	ds_read_b128 v[102:105], v247 offset:30720
	s_nop 0
	s_waitcnt lgkmcnt(4)
	v_mfma_f32_16x16x32_bf16 v[106:109], v[130:133], v[0:3], v[162:165]
	v_mfma_f32_16x16x32_bf16 v[110:113], v[134:137], v[0:3], v[166:169]
	v_mfma_f32_16x16x32_bf16 v[114:117], v[138:141], v[0:3], v[170:173]
	v_mfma_f32_16x16x32_bf16 v[130:133], v[142:145], v[0:3], v[174:177]
	s_nop 0
	v_add3_u32 v126, s24, v243, v241
	ds_read_b128 v[118:121], v126 offset:16384
	ds_read_b128 v[122:125], v126 offset:18432
	ds_read_b128 v[134:137], v126 offset:20480
	ds_read_b128 v[138:141], v126 offset:22528
	s_nop 0
	s_waitcnt lgkmcnt(5)
	v_mfma_f32_16x16x32_bf16 v[98:101], v[98:101], v[0:3], v[186:189]
	v_mfma_f32_16x16x32_bf16 v[8:11], v[8:11], v[0:3], v[178:181]
	v_mfma_f32_16x16x32_bf16 v[12:15], v[12:15], v[0:3], v[182:185]
	s_waitcnt lgkmcnt(4)
	v_mfma_f32_16x16x32_bf16 v[0:3], v[102:105], v[0:3], v[190:193]
	s_nop 0
	ds_read_b128 v[102:105], v126 offset:24576
	ds_read_b128 v[142:145], v126 offset:26624
	ds_read_b128 v[146:149], v126 offset:28672
	ds_read_b128 v[150:153], v126 offset:30720
	s_nop 0
	s_waitcnt lgkmcnt(7)
	v_mfma_f32_16x16x32_bf16 v[126:129], v[118:121], v[4:7], v[106:109]
	s_waitcnt lgkmcnt(6)
	v_mfma_f32_16x16x32_bf16 v[122:125], v[122:125], v[4:7], v[110:113]
	s_waitcnt lgkmcnt(5)
	v_mfma_f32_16x16x32_bf16 v[118:121], v[134:137], v[4:7], v[114:117]
	s_waitcnt lgkmcnt(4)
	v_mfma_f32_16x16x32_bf16 v[114:117], v[138:141], v[4:7], v[130:133]
	s_nop 0
	s_nop 0
	s_waitcnt lgkmcnt(3)
	v_mfma_f32_16x16x32_bf16 v[110:113], v[102:105], v[4:7], v[8:11]
	s_waitcnt lgkmcnt(2)
	v_mfma_f32_16x16x32_bf16 v[106:109], v[142:145], v[4:7], v[12:15]
	s_waitcnt lgkmcnt(1)
	v_mfma_f32_16x16x32_bf16 v[102:105], v[146:149], v[4:7], v[98:101]
	s_waitcnt lgkmcnt(0)
	v_mfma_f32_16x16x32_bf16 v[98:101], v[150:153], v[4:7], v[0:3]
	s_nop 0
	s_mov_b32 s6, 1
	s_mov_b64 s[14:15], 0
	s_and_b64 vcc, exec, s[4:5]
	s_cbranch_vccnz .LBB0_855

; DI void grid_bar(int* cnt, int target) {
;   __syncthreads();
;   if (threadIdx.x == 0) {
;     __builtin_amdgcn_fence(__ATOMIC_RELEASE, "agent");
;     asm volatile("s_waitcnt vmcnt(0)" ::: "memory");
;     __hip_atomic_fetch_add(cnt, 1, __ATOMIC_RELAXED, __HIP_MEMORY_SCOPE_AGENT);
;     while (__hip_atomic_load(cnt, __ATOMIC_RELAXED, __HIP_MEMORY_SCOPE_AGENT) < target) __builtin_amdgcn_s_sleep(2);
.LBB0_857:
	s_setprio 0
	s_barrier
	s_mov_b64 s[0:1], exec
	v_readlane_b32 s2, v255, 4
	v_readlane_b32 s3, v255, 5
	v_readlane_b32 s10, v255, 0
	s_and_b64 s[2:3], s[0:1], s[2:3]
	v_readlane_b32 s11, v255, 1
	s_mov_b64 exec, s[2:3]
	s_cbranch_execz .LBB0_863
	s_mov_b64 s[2:3], exec
	buffer_wbl2 sc1
	s_waitcnt vmcnt(0)
	s_waitcnt vmcnt(0)
	v_mbcnt_lo_u32_b32 v0, s2, 0
	v_mbcnt_hi_u32_b32 v0, s3, v0
	v_cmp_eq_u32_e32 vcc, 0, v0
	s_and_saveexec_b64 s[4:5], vcc
	s_cbranch_execz .LBB0_860
	s_bcnt1_i32_b64 s2, s[2:3]
	v_mov_b32_e32 v0, 0
	v_mov_b32_e32 v1, s2
	global_atomic_add v0, v1, s[10:11] offset:64
